# next-head expert word read from LDS at the top of the head loop body
# baseline (speedup 1.0000x reference)
.LBB0_330:
	v_add_u32_e32 v254, s24, v239
	ds_read_b32 v254, v254 offset:512
	s_waitcnt vmcnt(22)
	v_cvt_scalef32_pk32_f32_fp6 v[0:31], v[32:37], 1.0
	v_pk_fma_f32 v[0:1], v[0:1], v[152:153], 0 op_sel_hi:[1,1,0]
	v_pk_fma_f32 v[2:3], v[2:3], v[170:171], 0 op_sel_hi:[1,1,0]
	v_pk_fma_f32 v[0:1], v[4:5], v[148:149], v[0:1]
	v_pk_fma_f32 v[2:3], v[6:7], v[172:173], v[2:3]
	v_pk_fma_f32 v[0:1], v[8:9], v[144:145], v[0:1]
	v_pk_fma_f32 v[2:3], v[10:11], v[174:175], v[2:3]
	v_pk_fma_f32 v[0:1], v[12:13], v[140:141], v[0:1]
	v_pk_fma_f32 v[2:3], v[14:15], v[178:179], v[2:3]
	v_pk_fma_f32 v[0:1], v[16:17], v[168:169], v[0:1]
	v_pk_fma_f32 v[2:3], v[18:19], v[180:181], v[2:3]
	v_pk_fma_f32 v[0:1], v[20:21], v[164:165], v[0:1]
	v_pk_fma_f32 v[2:3], v[22:23], v[182:183], v[2:3]
	v_pk_fma_f32 v[0:1], v[24:25], v[160:161], v[0:1]
	v_pk_fma_f32 v[2:3], v[26:27], v[184:185], v[2:3]
	v_pk_fma_f32 v[0:1], v[28:29], v[156:157], v[0:1]
	v_pk_fma_f32 v[2:3], v[30:31], v[186:187], v[2:3]
	v_add_f32_e32 v4, v2, v3
	v_add_f32_e32 v5, v0, v1
	v_add_f32_e32 v117, v4, v5
	s_waitcnt vmcnt(20)
	v_cvt_scalef32_pk32_f32_fp6 v[0:31], v[38:43], 1.0
	v_pk_fma_f32 v[0:1], v[0:1], v[152:153], 0 op_sel_hi:[1,1,0]
	v_pk_fma_f32 v[2:3], v[2:3], v[170:171], 0 op_sel_hi:[1,1,0]
	v_pk_fma_f32 v[0:1], v[4:5], v[148:149], v[0:1]
	v_pk_fma_f32 v[2:3], v[6:7], v[172:173], v[2:3]
	v_pk_fma_f32 v[0:1], v[8:9], v[144:145], v[0:1]
	v_pk_fma_f32 v[2:3], v[10:11], v[174:175], v[2:3]
	v_pk_fma_f32 v[0:1], v[12:13], v[140:141], v[0:1]
	v_pk_fma_f32 v[2:3], v[14:15], v[178:179], v[2:3]
	v_pk_fma_f32 v[0:1], v[16:17], v[168:169], v[0:1]
	v_pk_fma_f32 v[2:3], v[18:19], v[180:181], v[2:3]
	v_pk_fma_f32 v[0:1], v[20:21], v[164:165], v[0:1]
	v_pk_fma_f32 v[2:3], v[22:23], v[182:183], v[2:3]
	v_pk_fma_f32 v[0:1], v[24:25], v[160:161], v[0:1]
	v_pk_fma_f32 v[2:3], v[26:27], v[184:185], v[2:3]
	v_pk_fma_f32 v[0:1], v[28:29], v[156:157], v[0:1]
	v_pk_fma_f32 v[2:3], v[30:31], v[186:187], v[2:3]
	v_add_f32_e32 v4, v2, v3
	v_add_f32_e32 v5, v0, v1
	v_add_f32_e32 v131, v4, v5
	s_waitcnt vmcnt(18)
	v_cvt_scalef32_pk32_f32_fp6 v[0:31], v[44:49], 1.0
	v_pk_fma_f32 v[0:1], v[0:1], v[152:153], 0 op_sel_hi:[1,1,0]
	v_pk_fma_f32 v[2:3], v[2:3], v[170:171], 0 op_sel_hi:[1,1,0]
	v_pk_fma_f32 v[0:1], v[4:5], v[148:149], v[0:1]
	v_pk_fma_f32 v[2:3], v[6:7], v[172:173], v[2:3]
	v_pk_fma_f32 v[0:1], v[8:9], v[144:145], v[0:1]
	v_pk_fma_f32 v[2:3], v[10:11], v[174:175], v[2:3]
	v_pk_fma_f32 v[0:1], v[12:13], v[140:141], v[0:1]
	v_pk_fma_f32 v[2:3], v[14:15], v[178:179], v[2:3]
	v_pk_fma_f32 v[0:1], v[16:17], v[168:169], v[0:1]
	v_pk_fma_f32 v[2:3], v[18:19], v[180:181], v[2:3]
	v_pk_fma_f32 v[0:1], v[20:21], v[164:165], v[0:1]
	v_pk_fma_f32 v[2:3], v[22:23], v[182:183], v[2:3]
	v_pk_fma_f32 v[0:1], v[24:25], v[160:161], v[0:1]
	v_pk_fma_f32 v[2:3], v[26:27], v[184:185], v[2:3]
	v_pk_fma_f32 v[0:1], v[28:29], v[156:157], v[0:1]
	v_pk_fma_f32 v[2:3], v[30:31], v[186:187], v[2:3]
	v_add_f32_e32 v4, v2, v3
	v_add_f32_e32 v5, v0, v1
	v_add_f32_e32 v133, v4, v5
	s_waitcnt vmcnt(16)
	v_cvt_scalef32_pk32_f32_fp6 v[0:31], v[50:55], 1.0
	v_pk_fma_f32 v[0:1], v[0:1], v[152:153], 0 op_sel_hi:[1,1,0]
	v_pk_fma_f32 v[2:3], v[2:3], v[170:171], 0 op_sel_hi:[1,1,0]
	v_pk_fma_f32 v[0:1], v[4:5], v[148:149], v[0:1]
	v_pk_fma_f32 v[2:3], v[6:7], v[172:173], v[2:3]
	v_pk_fma_f32 v[0:1], v[8:9], v[144:145], v[0:1]
	v_pk_fma_f32 v[2:3], v[10:11], v[174:175], v[2:3]
	v_pk_fma_f32 v[0:1], v[12:13], v[140:141], v[0:1]
	v_pk_fma_f32 v[2:3], v[14:15], v[178:179], v[2:3]
	v_pk_fma_f32 v[0:1], v[16:17], v[168:169], v[0:1]
	v_pk_fma_f32 v[2:3], v[18:19], v[180:181], v[2:3]
	v_pk_fma_f32 v[0:1], v[20:21], v[164:165], v[0:1]
	v_pk_fma_f32 v[2:3], v[22:23], v[182:183], v[2:3]
	v_pk_fma_f32 v[0:1], v[24:25], v[160:161], v[0:1]
	v_pk_fma_f32 v[2:3], v[26:27], v[184:185], v[2:3]
	v_pk_fma_f32 v[0:1], v[28:29], v[156:157], v[0:1]
	v_pk_fma_f32 v[2:3], v[30:31], v[186:187], v[2:3]
	v_add_f32_e32 v4, v2, v3
	v_add_f32_e32 v5, v0, v1
	v_add_f32_e32 v218, v4, v5
	s_waitcnt vmcnt(14)
	v_cvt_scalef32_pk32_f32_fp6 v[0:31], v[56:61], 1.0
	v_pk_fma_f32 v[0:1], v[0:1], v[152:153], 0 op_sel_hi:[1,1,0]
	v_pk_fma_f32 v[2:3], v[2:3], v[170:171], 0 op_sel_hi:[1,1,0]
	v_pk_fma_f32 v[0:1], v[4:5], v[148:149], v[0:1]
	v_pk_fma_f32 v[2:3], v[6:7], v[172:173], v[2:3]
	v_pk_fma_f32 v[0:1], v[8:9], v[144:145], v[0:1]
	v_pk_fma_f32 v[2:3], v[10:11], v[174:175], v[2:3]
	v_pk_fma_f32 v[0:1], v[12:13], v[140:141], v[0:1]
	v_pk_fma_f32 v[2:3], v[14:15], v[178:179], v[2:3]
	v_pk_fma_f32 v[0:1], v[16:17], v[168:169], v[0:1]
	v_pk_fma_f32 v[2:3], v[18:19], v[180:181], v[2:3]
	v_pk_fma_f32 v[0:1], v[20:21], v[164:165], v[0:1]
	v_pk_fma_f32 v[2:3], v[22:23], v[182:183], v[2:3]
	v_pk_fma_f32 v[0:1], v[24:25], v[160:161], v[0:1]
	v_pk_fma_f32 v[2:3], v[26:27], v[184:185], v[2:3]
	v_pk_fma_f32 v[0:1], v[28:29], v[156:157], v[0:1]
	v_pk_fma_f32 v[2:3], v[30:31], v[186:187], v[2:3]
	v_add_f32_e32 v4, v2, v3
	v_add_f32_e32 v5, v0, v1
	v_add_f32_e32 v219, v4, v5
	s_waitcnt vmcnt(12)
	v_cvt_scalef32_pk32_f32_fp6 v[0:31], v[62:67], 1.0
	v_pk_fma_f32 v[0:1], v[0:1], v[152:153], 0 op_sel_hi:[1,1,0]
	v_pk_fma_f32 v[2:3], v[2:3], v[170:171], 0 op_sel_hi:[1,1,0]
	v_pk_fma_f32 v[0:1], v[4:5], v[148:149], v[0:1]
	v_pk_fma_f32 v[2:3], v[6:7], v[172:173], v[2:3]
	v_pk_fma_f32 v[0:1], v[8:9], v[144:145], v[0:1]
	v_pk_fma_f32 v[2:3], v[10:11], v[174:175], v[2:3]
	v_pk_fma_f32 v[0:1], v[12:13], v[140:141], v[0:1]
	v_pk_fma_f32 v[2:3], v[14:15], v[178:179], v[2:3]
	v_pk_fma_f32 v[0:1], v[16:17], v[168:169], v[0:1]
	v_pk_fma_f32 v[2:3], v[18:19], v[180:181], v[2:3]
	v_pk_fma_f32 v[0:1], v[20:21], v[164:165], v[0:1]
	v_pk_fma_f32 v[2:3], v[22:23], v[182:183], v[2:3]
	v_pk_fma_f32 v[0:1], v[24:25], v[160:161], v[0:1]
	v_pk_fma_f32 v[2:3], v[26:27], v[184:185], v[2:3]
	v_pk_fma_f32 v[0:1], v[28:29], v[156:157], v[0:1]
	v_pk_fma_f32 v[2:3], v[30:31], v[186:187], v[2:3]
	v_add_f32_e32 v4, v2, v3
	v_add_f32_e32 v5, v0, v1
	v_add_f32_e32 v246, v4, v5
	s_waitcnt vmcnt(10)
	v_cvt_scalef32_pk32_f32_fp6 v[0:31], v[68:73], 1.0
	v_pk_fma_f32 v[0:1], v[0:1], v[152:153], 0 op_sel_hi:[1,1,0]
	v_pk_fma_f32 v[2:3], v[2:3], v[170:171], 0 op_sel_hi:[1,1,0]
	v_pk_fma_f32 v[0:1], v[4:5], v[148:149], v[0:1]
	v_pk_fma_f32 v[2:3], v[6:7], v[172:173], v[2:3]
	v_pk_fma_f32 v[0:1], v[8:9], v[144:145], v[0:1]
	v_pk_fma_f32 v[2:3], v[10:11], v[174:175], v[2:3]
	v_pk_fma_f32 v[0:1], v[12:13], v[140:141], v[0:1]
	v_pk_fma_f32 v[2:3], v[14:15], v[178:179], v[2:3]
	v_pk_fma_f32 v[0:1], v[16:17], v[168:169], v[0:1]
	v_pk_fma_f32 v[2:3], v[18:19], v[180:181], v[2:3]
	v_pk_fma_f32 v[0:1], v[20:21], v[164:165], v[0:1]
	v_pk_fma_f32 v[2:3], v[22:23], v[182:183], v[2:3]
	v_pk_fma_f32 v[0:1], v[24:25], v[160:161], v[0:1]
	v_pk_fma_f32 v[2:3], v[26:27], v[184:185], v[2:3]
	v_pk_fma_f32 v[0:1], v[28:29], v[156:157], v[0:1]
	v_pk_fma_f32 v[2:3], v[30:31], v[186:187], v[2:3]
	v_add_f32_e32 v4, v2, v3
	v_add_f32_e32 v5, v0, v1
	v_add_f32_e32 v247, v4, v5
	s_waitcnt vmcnt(8)
	v_cvt_scalef32_pk32_f32_fp6 v[0:31], v[74:79], 1.0
	v_pk_fma_f32 v[0:1], v[0:1], v[152:153], 0 op_sel_hi:[1,1,0]
	v_pk_fma_f32 v[2:3], v[2:3], v[170:171], 0 op_sel_hi:[1,1,0]
	v_pk_fma_f32 v[0:1], v[4:5], v[148:149], v[0:1]
	v_pk_fma_f32 v[2:3], v[6:7], v[172:173], v[2:3]
	v_pk_fma_f32 v[0:1], v[8:9], v[144:145], v[0:1]
	v_pk_fma_f32 v[2:3], v[10:11], v[174:175], v[2:3]
	v_pk_fma_f32 v[0:1], v[12:13], v[140:141], v[0:1]
	v_pk_fma_f32 v[2:3], v[14:15], v[178:179], v[2:3]
	v_pk_fma_f32 v[0:1], v[16:17], v[168:169], v[0:1]
	v_pk_fma_f32 v[2:3], v[18:19], v[180:181], v[2:3]
	v_pk_fma_f32 v[0:1], v[20:21], v[164:165], v[0:1]
	v_pk_fma_f32 v[2:3], v[22:23], v[182:183], v[2:3]
	v_pk_fma_f32 v[0:1], v[24:25], v[160:161], v[0:1]
	v_pk_fma_f32 v[2:3], v[26:27], v[184:185], v[2:3]
	v_pk_fma_f32 v[0:1], v[28:29], v[156:157], v[0:1]
	v_pk_fma_f32 v[2:3], v[30:31], v[186:187], v[2:3]
	v_add_f32_e32 v4, v2, v3
	v_add_f32_e32 v5, v0, v1
	v_add_f32_e32 v1, v4, v5
	v_add_u32_e32 v8, s24, v239
	s_waitcnt lgkmcnt(0)
	ds_bpermute_b32 v0, v255, v254
	ds_bpermute_b32 v2, v255, v254 offset:16
	ds_bpermute_b32 v3, v255, v254 offset:32
	ds_bpermute_b32 v6, v255, v254 offset:48
	ds_bpermute_b32 v7, v255, v254 offset:64
	ds_bpermute_b32 v10, v255, v254 offset:80
	ds_bpermute_b32 v11, v255, v254 offset:96
	ds_bpermute_b32 v14, v255, v254 offset:112
	s_waitcnt lgkmcnt(7)
	v_mad_i64_i32 v[22:23], s[2:3], v0, s28, v[118:119]
	global_load_dwordx2 v[36:37], v[22:23], off offset:16
	global_load_dwordx4 v[32:35], v[22:23], off
	s_waitcnt lgkmcnt(6)
	v_mad_i64_i32 v[24:25], s[2:3], v2, s28, v[118:119]
	global_load_dwordx2 v[42:43], v[24:25], off offset:16
	global_load_dwordx4 v[38:41], v[24:25], off
	s_waitcnt lgkmcnt(5)
	v_mad_i64_i32 v[22:23], s[2:3], v3, s28, v[118:119]
	global_load_dwordx2 v[48:49], v[22:23], off offset:16
	global_load_dwordx4 v[44:47], v[22:23], off
	s_waitcnt lgkmcnt(4)
	v_mad_i64_i32 v[24:25], s[2:3], v6, s28, v[118:119]
	global_load_dwordx2 v[54:55], v[24:25], off offset:16
	global_load_dwordx4 v[50:53], v[24:25], off
	s_waitcnt lgkmcnt(3)
	v_mad_i64_i32 v[22:23], s[2:3], v7, s28, v[118:119]
	global_load_dwordx2 v[60:61], v[22:23], off offset:16
	global_load_dwordx4 v[56:59], v[22:23], off
	s_waitcnt lgkmcnt(2)
	v_mad_i64_i32 v[24:25], s[2:3], v10, s28, v[118:119]
	global_load_dwordx2 v[66:67], v[24:25], off offset:16
	global_load_dwordx4 v[62:65], v[24:25], off
	s_waitcnt lgkmcnt(1)
	v_mad_i64_i32 v[22:23], s[2:3], v11, s28, v[118:119]
	global_load_dwordx2 v[72:73], v[22:23], off offset:16
	global_load_dwordx4 v[68:71], v[22:23], off
	s_waitcnt lgkmcnt(0)
	v_mad_i64_i32 v[24:25], s[2:3], v14, s28, v[118:119]
	global_load_dwordx2 v[78:79], v[24:25], off offset:16
	global_load_dwordx4 v[74:77], v[24:25], off
	ds_read_b64 v[16:17], v8
	s_nop 1
	v_permlane16_swap_b32_e32 v117, v219
	v_permlane16_swap_b32_e32 v131, v246
	v_permlane16_swap_b32_e32 v133, v247
	v_permlane16_swap_b32_e32 v218, v1
	v_add_f32_e32 v117, v117, v219
	v_add_f32_e32 v131, v131, v246
	v_add_f32_e32 v133, v133, v247
	v_add_f32_e32 v218, v218, v1
	s_nop 1
	v_add_f32_dpp v117, v117, v117 row_ror:8 row_mask:0xf bank_mask:0x3
	v_add_f32_dpp v117, v133, v133 row_ror:8 row_mask:0xf bank_mask:0xc
	v_add_f32_dpp v131, v131, v131 row_ror:8 row_mask:0xf bank_mask:0x3
	v_add_f32_dpp v131, v218, v218 row_ror:8 row_mask:0xf bank_mask:0xc
	s_nop 1
	v_add_f32_dpp v117, v117, v117 row_ror:12 row_mask:0xf bank_mask:0x5
	v_add_f32_dpp v117, v131, v131 row_ror:4 row_mask:0xf bank_mask:0xa
	s_nop 1
	v_add_f32_dpp v117, v117, v117 quad_perm:[2,3,0,1] row_mask:0xf bank_mask:0xf
	s_nop 1
	v_add_f32_dpp v1, v117, v117 quad_perm:[1,0,3,2] row_mask:0xf bank_mask:0xf
	s_waitcnt lgkmcnt(0)
	v_mul_f32_e32 v18, 0x3caaaaab, v1
	v_mul_f32_e32 v16, 0x3f3504f3, v18
	v_cmp_nlt_f32_e64 s[2:3], |v16|, 1.0
	s_and_saveexec_b64 s[26:27], s[2:3]
	s_xor_b64 s[2:3], exec, s[26:27]
	s_cbranch_execz .LBB0_332
	s_mov_b32 s25, 0x378e98ab
	v_fma_f32 v1, |v16|, s25, v233
	s_mov_b32 s25, 0x3b7cd369
	v_fma_f32 v1, |v16|, v1, s25
	s_mov_b32 s25, 0xbcc618b2
	v_fma_f32 v1, |v16|, v1, s25
	s_mov_b32 s25, 0x3dda74e4
	v_fma_f32 v1, |v16|, v1, s25
	s_mov_b32 s25, 0x3f228afd
	v_fma_f32 v1, |v16|, v1, s25
	s_mov_b32 s25, 0x3e03c728
	v_fma_f32 v1, |v16|, v1, s25
	v_fma_f32 v1, |v16|, v1, |v16|
	v_mul_f32_e32 v4, 0xbfb8aa3b, v1
	s_mov_b32 s25, 0xbfb8aa3b
	v_fma_f32 v5, v1, s25, -v4
	v_rndne_f32_e32 v8, v4
	v_fmac_f32_e32 v5, 0xb2a5705f, v1
	v_sub_f32_e32 v4, v4, v8
	v_add_f32_e32 v4, v4, v5
	v_cvt_i32_f32_e32 v5, v8
	v_exp_f32_e32 v4, v4
	s_mov_b32 s25, 0x42ce8ed0
	v_cmp_nlt_f32_e32 vcc, s25, v1
	s_mov_b32 s25, 0xc2b17218
	v_ldexp_f32 v4, v4, v5
	v_cndmask_b32_e32 v4, 0, v4, vcc
	v_cmp_ngt_f32_e32 vcc, s25, v1
	s_nop 1
	v_cndmask_b32_e32 v1, v234, v4, vcc
	v_sub_f32_e32 v19, 1.0, v1
